# attention unmasked loop: K/V LDS staging writes and next-tile global loads moved from the post-MFMA tail into PV MFMA gaps
# baseline (speedup 1.0000x reference)
; #define A_LOAD(t) do { _Pragma("unroll") for (int j_ = 0; j_ < 2; ++j_) { kreg[j_] = *(const u32x4*)(kg + (size_t)(64 * (t) + 32 * j_) * NIN); vreg[j_] = *(const u32x4*)(kg + 512 + (size_t)(64 * (t) + 32 * j_) * NIN); } } while (0)
; #define A_STORE(kbi, vbi) do { _Pragma("unroll") for (int j_ = 0; j_ < 2; ++j_) { *(LAS u32x4*)(lds + A_K0 + (kbi) * KBUF + (skey + 32 * j_) * KSTR + sch * 16) = kreg[j_]; *(LAS u32x4*)(lds + A_V0 + (vbi) * VBUF + (skey + 32 * j_) * VSTR + sch * 16) = vreg[j_]; } } while (0)
; __device__ __forceinline__ void attn_phase(LAS unsigned char* lds, const AttnArgs& a, int tid_in) {
;     ...
;         for (; t < NTM; ++t) {
;             A_PIPE(false, t, vp);
;             A_STORE((t + 1) & 1, vn);
;             if (t + 2 < NT) A_LOAD(t + 2);
.LBB0_581:
	s_setprio 1
	s_bitcmp1_b32 s4, 0
	s_cselect_b32 s30, 0x4400, 0
	v_add_u32_e32 v0, s30, v224
	ds_read_b128 v[2:5], v0
	ds_read_b128 v[6:9], v0 offset:32
	s_mul_i32 s30, s6, 0x5000
	s_waitcnt lgkmcnt(1)
	v_mfma_f32_32x32x16_bf16 v[128:143], v[2:5], v[144:147], v[96:111]
	ds_read_b128 v[2:5], v0 offset:8704
	ds_read_b128 v[10:13], v0 offset:8736
	s_waitcnt lgkmcnt(1)
	v_mfma_f32_32x32x16_bf16 v[112:127], v[2:5], v[144:147], v[96:111]
	v_mfma_f32_32x32x16_bf16 v[128:143], v[6:9], v[148:151], v[128:143]
	ds_read_b128 v[2:5], v0 offset:64
	ds_read_b128 v[6:9], v0 offset:96
	s_waitcnt lgkmcnt(2)
	v_mfma_f32_32x32x16_bf16 v[112:127], v[10:13], v[148:151], v[112:127]
	s_waitcnt lgkmcnt(1)
	v_mfma_f32_32x32x16_bf16 v[128:143], v[2:5], v[152:155], v[128:143]
	ds_read_b128 v[2:5], v0 offset:8768
	ds_read_b128 v[10:13], v0 offset:8800
	v_add_u32_e32 v0, s30, v225
	s_waitcnt lgkmcnt(1)
	v_mfma_f32_32x32x16_bf16 v[112:127], v[2:5], v[152:155], v[112:127]
	v_mfma_f32_32x32x16_bf16 v[128:143], v[6:9], v[156:159], v[128:143]
	ds_read_b64_tr_b16 v[2:3], v0 offset:34816
	ds_read_b64_tr_b16 v[6:7], v0 offset:34880
	ds_read_b64_tr_b16 v[236:237], v0 offset:34944
	ds_read_b64_tr_b16 v[240:241], v0 offset:35008
	ds_read_b64_tr_b16 v[4:5], v0 offset:37376
	ds_read_b64_tr_b16 v[8:9], v0 offset:37440
	ds_read_b64_tr_b16 v[238:239], v0 offset:37504
	ds_read_b64_tr_b16 v[242:243], v0 offset:37568
	s_waitcnt lgkmcnt(8)
	v_mfma_f32_32x32x16_bf16 v[112:127], v[10:13], v[156:159], v[112:127]
	s_waitcnt lgkmcnt(3)
	v_mfma_f32_32x32x16_bf16 v[64:79], v[188:191], v[2:5], v[64:79]
	ds_read_b64_tr_b16 v[2:3], v0 offset:39936
	ds_read_b64_tr_b16 v[4:5], v0 offset:42496
	v_exp_f32_e32 v128, v128
	v_exp_f32_e32 v129, v129
	v_exp_f32_e32 v130, v130
	v_add_f32_e32 v17, v128, v129
	s_waitcnt lgkmcnt(4)
	v_mfma_f32_32x32x16_bf16 v[80:95], v[188:191], v[6:9], v[80:95]
	ds_read_b64_tr_b16 v[6:7], v0 offset:40000
	ds_read_b64_tr_b16 v[8:9], v0 offset:42560
	v_exp_f32_e32 v131, v131
	v_exp_f32_e32 v132, v132
	v_exp_f32_e32 v133, v133
	v_add_f32_e32 v17, v17, v130
	s_waitcnt lgkmcnt(5)
	v_mfma_f32_32x32x16_bf16 v[48:63], v[188:191], v[236:239], v[48:63]
	ds_read_b64_tr_b16 v[10:11], v0 offset:40064
	ds_read_b64_tr_b16 v[12:13], v0 offset:42624
	v_exp_f32_e32 v134, v134
	v_exp_f32_e32 v135, v135
	v_exp_f32_e32 v136, v136
	v_add_f32_e32 v17, v17, v131
	s_waitcnt lgkmcnt(6)
	v_mfma_f32_32x32x16_bf16 v[32:47], v[188:191], v[240:243], v[32:47]
	ds_read_b64_tr_b16 v[28:29], v0 offset:40128
	ds_read_b64_tr_b16 v[30:31], v0 offset:42688
	v_exp_f32_e32 v137, v137
	v_exp_f32_e32 v138, v138
	v_exp_f32_e32 v139, v139
	v_cvt_pk_bf16_f32 v188, v128, v129
	s_waitcnt lgkmcnt(6)
	v_mfma_f32_32x32x16_bf16 v[64:79], v[184:187], v[2:5], v[64:79]
	ds_read_b64_tr_b16 v[2:3], v0 offset:45056
	ds_read_b64_tr_b16 v[4:5], v0 offset:47616
	v_exp_f32_e32 v140, v140
	v_exp_f32_e32 v141, v141
	v_exp_f32_e32 v142, v142
	v_cvt_pk_bf16_f32 v189, v130, v131
	s_waitcnt lgkmcnt(6)
	v_mfma_f32_32x32x16_bf16 v[80:95], v[184:187], v[6:9], v[80:95]
	ds_read_b64_tr_b16 v[6:7], v0 offset:45120
	ds_read_b64_tr_b16 v[8:9], v0 offset:47680
	v_exp_f32_e32 v143, v143
	v_exp_f32_e32 v112, v112
	v_exp_f32_e32 v113, v113
	v_cvt_pk_bf16_f32 v190, v132, v133
	s_waitcnt lgkmcnt(6)
	v_mfma_f32_32x32x16_bf16 v[48:63], v[184:187], v[10:13], v[48:63]
	ds_read_b64_tr_b16 v[10:11], v0 offset:45184
	ds_read_b64_tr_b16 v[12:13], v0 offset:47744
	v_exp_f32_e32 v114, v114
	v_exp_f32_e32 v115, v115
	v_exp_f32_e32 v116, v116
	v_cvt_pk_bf16_f32 v191, v134, v135
	s_waitcnt lgkmcnt(6)
	v_mfma_f32_32x32x16_bf16 v[32:47], v[184:187], v[28:31], v[32:47]
	ds_read_b64_tr_b16 v[28:29], v0 offset:45248
	ds_read_b64_tr_b16 v[30:31], v0 offset:47808
	s_andn2_b32 s30, 1, s4
	s_mulk_i32 s30, 0x4400
	s_mul_i32 s31, s34, 0x5000
	v_add3_u32 v21, v223, s30, v228
	v_add3_u32 v22, v223, s31, v229
	v_exp_f32_e32 v117, v117
	v_exp_f32_e32 v118, v118
	v_exp_f32_e32 v119, v119
	v_cvt_pk_bf16_f32 v184, v136, v137
	s_waitcnt lgkmcnt(6)
	v_mfma_f32_32x32x16_bf16 v[64:79], v[180:183], v[2:5], v[64:79]
	ds_read_b64_tr_b16 v[2:3], v0 offset:50176
	ds_read_b64_tr_b16 v[4:5], v0 offset:52736
	s_waitcnt vmcnt(3)
	ds_write_b128 v21, v[160:163]
	v_exp_f32_e32 v120, v120
	v_exp_f32_e32 v121, v121
	v_exp_f32_e32 v122, v122
	v_cvt_pk_bf16_f32 v185, v138, v139
	s_waitcnt lgkmcnt(7)
	v_mfma_f32_32x32x16_bf16 v[80:95], v[180:183], v[6:9], v[80:95]
	ds_read_b64_tr_b16 v[6:7], v0 offset:50240
	ds_read_b64_tr_b16 v[8:9], v0 offset:52800
	s_waitcnt vmcnt(2)
	ds_write_b128 v22, v[164:167] offset:34816
	v_exp_f32_e32 v123, v123
	v_exp_f32_e32 v124, v124
	v_exp_f32_e32 v125, v125
	v_cvt_pk_bf16_f32 v186, v140, v141
	s_waitcnt lgkmcnt(8)
	v_mfma_f32_32x32x16_bf16 v[48:63], v[180:183], v[10:13], v[48:63]
	ds_read_b64_tr_b16 v[10:11], v0 offset:50304
	ds_read_b64_tr_b16 v[12:13], v0 offset:52864
	s_waitcnt vmcnt(1)
	ds_write_b128 v21, v[168:171] offset:8704
	v_exp_f32_e32 v126, v126
	v_exp_f32_e32 v127, v127
	v_cvt_pk_bf16_f32 v187, v142, v143
	v_add_f32_e32 v17, v17, v132
	v_add_f32_e32 v17, v17, v133
	s_waitcnt lgkmcnt(9)
	v_mfma_f32_32x32x16_bf16 v[32:47], v[180:183], v[28:31], v[32:47]
	ds_read_b64_tr_b16 v[28:29], v0 offset:50368
	ds_read_b64_tr_b16 v[30:31], v0 offset:52928
	s_waitcnt vmcnt(0)
	ds_write_b128 v22, v[172:175] offset:45056
	v_cvt_pk_bf16_f32 v180, v112, v113
	v_cvt_pk_bf16_f32 v181, v114, v115
	v_cvt_pk_bf16_f32 v182, v116, v117
	v_cvt_pk_bf16_f32 v183, v118, v119
	v_add_f32_e32 v17, v17, v134
	v_add_f32_e32 v17, v17, v135
	v_add_f32_e32 v18, v136, v137
	s_waitcnt lgkmcnt(10)
	v_mfma_f32_32x32x16_bf16 v[64:79], v[176:179], v[2:5], v[64:79]
	v_add_f32_e32 v18, v18, v138
	v_add_f32_e32 v18, v18, v139
	v_add_f32_e32 v18, v18, v140
	v_add_f32_e32 v18, v18, v141
	v_add_f32_e32 v18, v18, v142
	v_add_f32_e32 v18, v18, v143
	v_add_f32_e32 v19, v112, v113
	s_waitcnt lgkmcnt(7)
	v_mfma_f32_32x32x16_bf16 v[80:95], v[176:179], v[6:9], v[80:95]
	v_add_f32_e32 v19, v19, v114
	v_add_f32_e32 v19, v19, v115
	v_add_f32_e32 v19, v19, v116
	v_add_f32_e32 v19, v19, v117
	v_add_f32_e32 v19, v19, v118
	v_add_f32_e32 v19, v19, v119
	v_add_f32_e32 v20, v120, v121
	s_add_i32 s30, s4, 2
	s_cmp_ge_i32 s30, s27
	s_cbranch_scc1 .Lattn_u_skipld
	s_sub_i32 s30, s5, 32
	v_mad_u64_u32 v[24:25], s[30:31], s30, v219, v[202:203]
	v_mad_u64_u32 v[26:27], s[30:31], s5, v219, v[202:203]
	global_load_dwordx4 v[160:163], v[24:25], off
	global_load_dwordx4 v[164:167], v[24:25], off offset:1024
	global_load_dwordx4 v[168:171], v[26:27], off
	global_load_dwordx4 v[172:175], v[26:27], off offset:1024
; #define A_LOAD(t) do { _Pragma("unroll") for (int j_ = 0; j_ < 2; ++j_) { kreg[j_] = *(const u32x4*)(kg + (size_t)(64 * (t) + 32 * j_) * NIN); vreg[j_] = *(const u32x4*)(kg + 512 + (size_t)(64 * (t) + 32 * j_) * NIN); } } while (0)
; #define A_STORE(kbi, vbi) do { _Pragma("unroll") for (int j_ = 0; j_ < 2; ++j_) { *(LAS u32x4*)(lds + A_K0 + (kbi) * KBUF + (skey + 32 * j_) * KSTR + sch * 16) = kreg[j_]; *(LAS u32x4*)(lds + A_V0 + (vbi) * VBUF + (skey + 32 * j_) * VSTR + sch * 16) = vreg[j_]; } } while (0)
; __device__ __forceinline__ void attn_phase(LAS unsigned char* lds, const AttnArgs& a, int tid_in) {
;     ...
;             A_STORE((t + 1) & 1, vn);
;             if (t + 2 < NT) A_LOAD(t + 2);
;             __syncthreads();
;             vp = (vp == 2) ? 0 : vp + 1; vn = (vn == 2) ? 0 : vn + 1;
;         }
.Lattn_u_skipld:
	s_waitcnt lgkmcnt(4)
	v_mfma_f32_32x32x16_bf16 v[48:63], v[176:179], v[10:13], v[48:63]
	v_add_f32_e32 v20, v20, v122
	v_add_f32_e32 v20, v20, v123
	v_add_f32_e32 v20, v20, v124
	v_add_f32_e32 v20, v20, v125
	v_add_f32_e32 v20, v20, v126
	v_add_f32_e32 v20, v20, v127
	v_add_f32_e32 v17, v17, v18
	s_waitcnt lgkmcnt(1)
	v_mfma_f32_32x32x16_bf16 v[32:47], v[176:179], v[28:31], v[32:47]
	v_cvt_pk_bf16_f32 v176, v120, v121
	v_cvt_pk_bf16_f32 v177, v122, v123
	v_cvt_pk_bf16_f32 v178, v124, v125
	v_cvt_pk_bf16_f32 v179, v126, v127
	v_add_f32_e32 v19, v19, v20
	v_add_f32_e32 v17, v17, v19
	v_add_f32_e32 v211, v211, v17
	s_setprio 0
	s_add_i32 s30, s6, 1
	s_cmp_lg_u32 s6, 2
	s_cselect_b32 s6, s30, 0
	s_add_i32 s30, s34, 1
	s_cmp_lg_u32 s34, 2
	s_cselect_b32 s34, s30, 0
	s_add_i32 s4, s4, 1
	s_add_i32 s5, s5, 64
	s_cmp_eq_u32 s35, s4
	s_waitcnt lgkmcnt(0)
	s_barrier
	s_cbranch_scc0 .LBB0_581
	s_branch .LBB0_584
